# P9 epilogue: wave owns 64 contiguous columns, SZ loaded 8 rows x 128B per instruction and redistributed with ds_bpermute
# baseline (speedup 1.0000x reference)
;     __device__ __forceinline__ bool next(int i, Unit& u) const { const int L = i * G + c; if (L >= nM * nN) return false; static_unit(L, nM, nN, u.pm, u.pn); u.grp = 0; return true; }
;     __device__ __forceinline__ bool next(int i, Unit& u) const { const int L = i * G + c; if (L >= 256) return false; const int cu = L >> 2; u.grp = L & 3; u.pm = 64 + (cu >> 5); u.pn = cu & 31; return true; }
; #define PG8_WAIT_V(n) asm volatile("s_waitcnt vmcnt(" #n ")" ::: "memory")
; template <class Epi, class Sched>
; __device__ __forceinline__ void gemm_phase(PG8_LAS unsigned char* lds, const Gemm g, const Sched& S, const Epi& E, int wave_) {
;     ...
;     for (int i = 0; i < 2; ++i) { int R, C; stage_rc(tid * 16 + i * 8192, R, C); const int Rb = Epi::PERM ? ((R & ~31) + perm32(R & 31)) : R;
;         voffA[i] = g.a_gm == 2 ? (unsigned)(((C >> 3) * SEQ + R) * 16) : g.a_gm ? (unsigned)(((C >> 4) * SEQ + R) * 32 + (C & 15) * 2) : (unsigned)(R * g.lda + C) * 2u; voffB[i] = (unsigned)(Rb * g.ldb + C) * 2u; }
;     const int gmb = g.a_gm == 2 ? 16 : 32;
;     const size_t kstep = (size_t)(BK * 2), kstepA = g.a_gm ? (size_t)(128 / gmb) * SEQ * gmb : kstep;
;     const size_t hsA = g.a_gm ? (size_t)HALF * gmb : (size_t)HALF * g.lda * 2, hsB = (size_t)HALF * g.ldb * 2;
;     ...
;     const unsigned ldsw = (unsigned)wid * 1024u;
;     const int aoff = lds_byte(wr * 64 + fr, fq * 8), boff = lds_byte(wc * 32 + fr, fq * 8);
;     ...
;     Unit cur, nxt; int ui = 0;
;     if (!S.next(0, cur)) return;
;     f32x4 acc[2][2][4][2];
; #pragma unroll
;     for (int a = 0; a < 2; ++a)
; #pragma unroll
;         for (int b = 0; b < 2; ++b)
; #pragma unroll
;             for (int m = 0; m < 4; ++m)
; #pragma unroll
;                 for (int n = 0; n < 2; ++n) acc[a][b][m][n] = (f32x4){0.f, 0.f, 0.f, 0.f};
;     i32x8 At[4], B0[2], B1[2];
;     const char* cA = PG8_PANEL_A(cur); const char* cB = (const char*)(g.Bt + (size_t)cur.grp * g.b_gs) + (size_t)cur.pn * 2 * hsB;
;     PG8_STAGE(PG8_SB(0, 0), cB, voffB); PG8_STAGE(PG8_SB(0, 1), cB + hsB, voffB); PG8_STAGE(PG8_SA(0, 0), cA, voffA); PG8_STAGE(PG8_SA(0, 1), cA + hsA, voffA);
;     if (wr == 1) PG8_BAR;
;     PG8_WAIT_V(2); PG8_BAR;
;     PG8_STAGE(PG8_SB(1, 0), cB + kstep, voffB); PG8_STAGE(PG8_SA(1, 0), cA + kstepA, voffA); PG8_STAGE(PG8_SB(1, 1), cB + hsB + kstep, voffB); PG8_STAGE(PG8_SA(1, 1), cA + kstepA + hsA, voffA);
;     PG8_WAIT_V(0); PG8_BAR;
.LBB0_1028:
	s_add_u32 s10, s30, 0x3c400000
	s_addc_u32 s11, s31, 0
	s_add_u32 s12, s30, 0x2bc00000
	s_addc_u32 s13, s31, 0
	s_lshl_b32 s16, s95, 5
	s_and_b32 s38, s16, 0x60
	s_lshl_b32 s21, s20, 13
	s_lshr_b32 s39, s38, 3
	s_add_u32 s22, s56, 0x80080
	s_addc_u32 s23, s57, 0
	s_add_u32 s36, s54, 0x200080
	s_addc_u32 s37, s55, 0
	v_readlane_b32 s16, v252, 0
	s_cmpk_lt_u32 s16, 0x100
	s_cselect_b64 s[16:17], -1, 0
	s_mov_b64 s[18:19], 0x80
	s_add_i32 s73, s35, 0x18000
	v_lshl_add_u64 v[6:7], v[6:7], 0, s[18:19]
	s_mov_b32 m0, s73
	s_add_i32 s74, s35, 0x1a000
	s_waitcnt vmcnt(2)
	s_barrier
	global_load_lds_dwordx4 v[6:7], off
	v_lshl_add_u64 v[4:5], v[4:5], 0, s[18:19]
	s_mov_b32 m0, s74
	s_add_i32 s75, s35, 0x8000
	global_load_lds_dwordx4 v[4:5], off
	v_lshl_add_u64 v[2:3], v[2:3], 0, s[18:19]
	s_mov_b32 m0, s75
	s_add_i32 s76, s35, 0xa000
	global_load_lds_dwordx4 v[2:3], off
	v_lshl_add_u64 v[0:1], v[0:1], 0, s[18:19]
	s_mov_b32 m0, s76
	s_add_i32 s77, s35, 0x1c000
	global_load_lds_dwordx4 v[0:1], off
	v_lshl_add_u64 v[0:1], s[22:23], 0, v[196:197]
	s_mov_b32 m0, s77
	s_add_i32 s78, s35, 0x1e000
	global_load_lds_dwordx4 v[0:1], off
	v_lshl_add_u64 v[0:1], s[22:23], 0, v[192:193]
	s_mov_b32 m0, s78
	s_add_i32 s79, s35, 0xc000
	global_load_lds_dwordx4 v[0:1], off
	v_lshl_add_u64 v[0:1], s[36:37], 0, v[198:199]
	s_mov_b32 m0, s79
	s_add_i32 s80, s35, 0xe000
	global_load_lds_dwordx4 v[0:1], off
	v_lshl_add_u64 v[0:1], s[36:37], 0, v[194:195]
	s_mov_b32 m0, s80
	v_and_b32_e32 v3, 48, v8
	global_load_lds_dwordx4 v[0:1], off
	v_and_b32_e32 v0, 15, v8
	v_lshl_or_b32 v216, s20, 6, v0
	v_lshl_or_b32 v0, v0, 6, v3
	v_lshlrev_b32_e32 v3, 2, v8
	v_ashrrev_i32_e32 v2, 6, v8
	v_and_b32_e32 v3, 32, v3
	v_add_u32_e32 v4, s39, v2
	v_xad_u32 v0, v0, v3, 0
	v_ashrrev_i32_e32 v1, 1, v8
	v_lshl_add_u32 v3, v4, 10, v0
	v_lshl_add_u32 v3, s39, 10, v3
	v_lshl_add_u32 v2, v2, 10, v0
	v_lshlrev_b32_e32 v0, 17, v12
	v_and_b32_e32 v1, -8, v1
	v_and_b32_e32 v0, 0xfffc0000, v0
	v_add_u32_e32 v221, s38, v1
	v_add_u32_e32 v221, s38, v221
	v_lshl_add_u32 v0, v13, 14, v0
	v_and_b32_e32 v1, 1, v12
	v_lshl_or_b32 v0, v1, 6, v0
	s_mov_b64 s[22:23], 0x200080
	v_lshl_add_u32 v0, v14, 1, v0
	v_mov_b32_e32 v1, v197
	v_lshl_add_u64 v[200:201], v[0:1], 0, s[22:23]
	v_lshlrev_b32_e32 v0, 17, v9
	v_and_b32_e32 v0, 0xfffc0000, v0
	v_lshl_add_u32 v0, v10, 14, v0
	v_and_b32_e32 v1, 1, v9
	s_waitcnt vmcnt(0)
	v_lshl_or_b32 v0, v1, 6, v0
	v_lshl_add_u32 v0, v11, 1, v0
	v_mov_b32_e32 v1, v197
	v_add_u32_e32 v217, 0x10000, v3
	v_add_u32_e32 v218, 0x11000, v3
	v_add_u32_e32 v219, 0x18000, v3
	v_add_u32_e32 v220, 0x19000, v3
	v_add_u32_e32 v222, 0x10400, v3
	v_add_u32_e32 v223, 0x10800, v3
	v_add_u32_e32 v224, 0x10c00, v3
	v_add_u32_e32 v225, 0x11400, v3
	v_add_u32_e32 v226, 0x11800, v3
	v_add_u32_e32 v227, 0x11c00, v3
	v_add_u32_e32 v228, 0x18400, v3
	v_add_u32_e32 v229, 0x18800, v3
	v_add_u32_e32 v230, 0x18c00, v3
	v_add_u32_e32 v231, 0x19400, v3
	v_add_u32_e32 v232, 0x19800, v3
	v_add_u32_e32 v233, 0x19c00, v3
	v_lshl_add_u64 v[202:203], v[0:1], 0, s[22:23]
	v_add_u32_e32 v234, s21, v2
	s_mov_b64 s[20:21], 0x240000
	s_mov_b64 s[22:23], 0x280000
	s_mov_b64 s[36:37], 0x2c0000
	s_barrier
	s_branch .LBB0_1031

; __device__ __forceinline__ unsigned cvt_pk_bf16(float lo, float hi) { unsigned r; asm volatile("v_cvt_pk_bf16_f32 %0, %1, %2" : "=v"(r) : "v"(lo), "v"(hi)); return r; }
; __device__ __forceinline__ float bf_lo(unsigned w) { return __uint_as_float(w << 16); }
; __device__ __forceinline__ float bf_hi(unsigned w) { return __uint_as_float(w & 0xffff0000u); }
;     __device__ __forceinline__ void operator()(const f32x4 (&acc)[2][2][4][2], const Unit& u, int wr, int wc, int fr, int fq) const {
;         const int row0 = u.pm * BM + wr * 64 + fr, col0 = u.grp * 2048 + u.pn * BM + wc * 32 + 8 * fq;
;         f32x4 sv[2][2];
; #pragma unroll
;         for (int bj = 0; bj < 2; ++bj)
; #pragma unroll
;             for (int n = 0; n < 2; ++n) sv[bj][n] = *(const f32x4*)(scale + col0 + bj * HALF + 4 * n);
; #pragma unroll
;         for (int ai = 0; ai < 2; ++ai)
; #pragma unroll
;             for (int m = 0; m < 4; ++m) { const size_t off = (size_t)(row0 + ai * HALF + m * 16) * EI + col0;
; #pragma unroll
;                 for (int bj = 0; bj < 2; ++bj) { const u32x4 zv = *(const u32x4*)(SZ + off + bj * HALF);
;                     const f32x4 g0 = acc[ai][bj][m][0] * sv[bj][0], g1 = acc[ai][bj][m][1] * sv[bj][1];
;                     u32x4 w; w.x = cvt_pk_bf16(g0[0] * bf_lo(zv.x), g0[1] * bf_hi(zv.x)); w.y = cvt_pk_bf16(g0[2] * bf_lo(zv.y), g0[3] * bf_hi(zv.y));
;                     w.z = cvt_pk_bf16(g1[0] * bf_lo(zv.z), g1[1] * bf_hi(zv.z)); w.w = cvt_pk_bf16(g1[2] * bf_lo(zv.w), g1[3] * bf_hi(zv.w));
;                     *(u32x4*)(V + off + bj * HALF) = w; } }
.LBB0_1049:
	s_lshl_b32 s39, s52, 11
	s_lshl_b32 s41, s82, 8
	s_add_i32 s41, s41, s39
	v_lshl_add_u32 v148, s81, 8, v216
	v_add_u32_e32 v146, s41, v221
	v_ashrrev_i32_e32 v149, 31, v148
	v_ashrrev_i32_e32 v147, 31, v146
	v_lshlrev_b64 v[104:105], 13, v[148:149]
	v_lshl_add_u64 v[108:109], v[146:147], 2, s[24:25]
	v_lshl_add_u64 v[104:105], v[104:105], 0, v[146:147]
	global_load_dwordx4 v[128:131], v[108:109], off offset:16
	global_load_dwordx4 v[132:135], v[108:109], off
	v_lshlrev_b64 v[144:145], 1, v[104:105]
	global_load_dwordx4 v[104:107], v[108:109], off offset:144
	s_nop 0
	global_load_dwordx4 v[108:111], v[108:109], off offset:128
	s_andn2_b64 vcc, exec, s[50:51]
	s_mov_b64 s[50:51], -1
	v_and_b32_e32 v157, 15, v216
	v_bfe_u32 v158, v221, 3, 2
	s_lshl_b32 s39, s81, 8
	v_and_b32_e32 v159, 0xfffffff0, v216
	v_lshrrev_b32_e32 v156, 3, v157
	v_lshl_add_u32 v156, v158, 1, v156
	v_add3_u32 v159, v159, s39, v156
	v_and_b32_e32 v156, 0xffffffc0, v221
	v_add_u32_e32 v156, s41, v156
	v_lshlrev_b32_e32 v156, 1, v156
	v_lshl_add_u32 v145, v159, 14, v156
	v_and_b32_e32 v159, 7, v157
	v_lshl_add_u32 v145, v159, 4, v145
	v_lshl_add_u32 v146, v159, 3, v158
	v_lshlrev_b32_e32 v146, 2, v146
	v_add_u32_e32 v147, 16, v146
	s_mov_b32 s54, 0xff00ff00
	s_mov_b32 s55, 0xff00ff00
	global_load_dwordx4 v[160:163], v145, s[10:11]
	v_add_u32_e32 v156, 0x20000, v145
	global_load_dwordx4 v[164:167], v156, s[10:11]
	v_add_u32_e32 v145, 0x40000, v145
	global_load_dwordx4 v[168:171], v145, s[10:11]
	v_add_u32_e32 v156, 0x20000, v145
	global_load_dwordx4 v[172:175], v156, s[10:11]
	v_add_u32_e32 v145, 0x40000, v145
	global_load_dwordx4 v[176:179], v145, s[10:11]
	v_add_u32_e32 v156, 0x20000, v145
	global_load_dwordx4 v[180:183], v156, s[10:11]
	v_add_u32_e32 v145, 0x40000, v145
	global_load_dwordx4 v[184:187], v145, s[10:11]
	v_add_u32_e32 v156, 0x20000, v145
	global_load_dwordx4 v[188:191], v156, s[10:11]
	v_add_u32_e32 v145, 0x140000, v145
	s_waitcnt vmcnt(8)
	v_pk_mul_f32 v[138:139], v[138:139], v[130:131]
	v_pk_mul_f32 v[142:143], v[142:143], v[134:135]
	v_pk_mul_f32 v[140:141], v[140:141], v[132:133]
	v_pk_mul_f32 v[136:137], v[136:137], v[128:129]
	v_pk_mul_f32 v[118:119], v[118:119], v[106:107]
	v_pk_mul_f32 v[126:127], v[126:127], v[110:111]
	v_pk_mul_f32 v[124:125], v[124:125], v[108:109]
	v_pk_mul_f32 v[116:117], v[116:117], v[104:105]
	v_pk_mul_f32 v[122:123], v[122:123], v[134:135]
	v_pk_mul_f32 v[120:121], v[120:121], v[132:133]
	v_pk_mul_f32 v[114:115], v[114:115], v[130:131]
	v_pk_mul_f32 v[112:113], v[112:113], v[128:129]
	v_pk_mul_f32 v[94:95], v[94:95], v[106:107]
	v_pk_mul_f32 v[102:103], v[102:103], v[110:111]
	v_pk_mul_f32 v[100:101], v[100:101], v[108:109]
	v_pk_mul_f32 v[92:93], v[92:93], v[104:105]
	v_pk_mul_f32 v[98:99], v[98:99], v[134:135]
	v_pk_mul_f32 v[96:97], v[96:97], v[132:133]
	v_pk_mul_f32 v[90:91], v[90:91], v[130:131]
	v_pk_mul_f32 v[88:89], v[88:89], v[128:129]
	v_pk_mul_f32 v[78:79], v[78:79], v[106:107]
	v_pk_mul_f32 v[86:87], v[86:87], v[110:111]
	v_pk_mul_f32 v[84:85], v[84:85], v[108:109]
	v_pk_mul_f32 v[76:77], v[76:77], v[104:105]
	v_pk_mul_f32 v[82:83], v[82:83], v[134:135]
	v_pk_mul_f32 v[80:81], v[80:81], v[132:133]
	v_pk_mul_f32 v[74:75], v[74:75], v[130:131]
	v_pk_mul_f32 v[72:73], v[72:73], v[128:129]
	v_pk_mul_f32 v[66:67], v[66:67], v[106:107]
	v_pk_mul_f32 v[70:71], v[70:71], v[110:111]
	v_pk_mul_f32 v[68:69], v[68:69], v[108:109]
	v_pk_mul_f32 v[64:65], v[64:65], v[104:105]
	v_pk_mul_f32 v[62:63], v[62:63], v[134:135]
	v_pk_mul_f32 v[60:61], v[60:61], v[132:133]
	v_pk_mul_f32 v[58:59], v[58:59], v[130:131]
	v_pk_mul_f32 v[56:57], v[56:57], v[128:129]
	v_pk_mul_f32 v[46:47], v[46:47], v[106:107]
	v_pk_mul_f32 v[54:55], v[54:55], v[110:111]
	v_pk_mul_f32 v[52:53], v[52:53], v[108:109]
	v_pk_mul_f32 v[44:45], v[44:45], v[104:105]
	v_pk_mul_f32 v[50:51], v[50:51], v[134:135]
	v_pk_mul_f32 v[48:49], v[48:49], v[132:133]
	v_pk_mul_f32 v[42:43], v[42:43], v[130:131]
	v_pk_mul_f32 v[40:41], v[40:41], v[128:129]
	v_pk_mul_f32 v[30:31], v[30:31], v[106:107]
	v_pk_mul_f32 v[38:39], v[38:39], v[110:111]
	v_pk_mul_f32 v[36:37], v[36:37], v[108:109]
	v_pk_mul_f32 v[28:29], v[28:29], v[104:105]
	v_pk_mul_f32 v[34:35], v[34:35], v[134:135]
	v_pk_mul_f32 v[32:33], v[32:33], v[132:133]
	v_pk_mul_f32 v[26:27], v[26:27], v[130:131]
	v_pk_mul_f32 v[24:25], v[24:25], v[128:129]
	v_pk_mul_f32 v[14:15], v[14:15], v[106:107]
	v_pk_mul_f32 v[22:23], v[22:23], v[110:111]
	v_pk_mul_f32 v[20:21], v[20:21], v[108:109]
	v_pk_mul_f32 v[12:13], v[12:13], v[104:105]
	v_pk_mul_f32 v[18:19], v[18:19], v[134:135]
	v_pk_mul_f32 v[16:17], v[16:17], v[132:133]
	v_pk_mul_f32 v[10:11], v[10:11], v[130:131]
	v_pk_mul_f32 v[8:9], v[8:9], v[128:129]
	v_pk_mul_f32 v[2:3], v[2:3], v[106:107]
	v_pk_mul_f32 v[6:7], v[6:7], v[110:111]
	v_pk_mul_f32 v[4:5], v[4:5], v[108:109]
	v_pk_mul_f32 v[0:1], v[0:1], v[104:105]
	s_waitcnt vmcnt(6)
	ds_bpermute_b32 v104, v146, v160
	ds_bpermute_b32 v108, v146, v164
	ds_bpermute_b32 v105, v146, v161
	ds_bpermute_b32 v109, v146, v165
	ds_bpermute_b32 v106, v146, v162
	ds_bpermute_b32 v110, v146, v166
	ds_bpermute_b32 v107, v146, v163
	ds_bpermute_b32 v111, v146, v167
	ds_bpermute_b32 v128, v147, v160
	ds_bpermute_b32 v132, v147, v164
	ds_bpermute_b32 v129, v147, v161
	ds_bpermute_b32 v133, v147, v165
	ds_bpermute_b32 v130, v147, v162
	ds_bpermute_b32 v134, v147, v166
	ds_bpermute_b32 v131, v147, v163
	ds_bpermute_b32 v135, v147, v167
	s_waitcnt lgkmcnt(8)
; __device__ __forceinline__ unsigned cvt_pk_bf16(float lo, float hi) { unsigned r; asm volatile("v_cvt_pk_bf16_f32 %0, %1, %2" : "=v"(r) : "v"(lo), "v"(hi)); return r; }
; __device__ __forceinline__ float bf_lo(unsigned w) { return __uint_as_float(w << 16); }
; __device__ __forceinline__ float bf_hi(unsigned w) { return __uint_as_float(w & 0xffff0000u); }
;     __device__ __forceinline__ void operator()(const f32x4 (&acc)[2][2][4][2], const Unit& u, int wr, int wc, int fr, int fq) const {
;     ...
;         for (int ai = 0; ai < 2; ++ai)
; #pragma unroll
;             for (int m = 0; m < 4; ++m) { const size_t off = (size_t)(row0 + ai * HALF + m * 16) * EI + col0;
; #pragma unroll
;                 for (int bj = 0; bj < 2; ++bj) { const u32x4 zv = *(const u32x4*)(SZ + off + bj * HALF);
;                     const f32x4 g0 = acc[ai][bj][m][0] * sv[bj][0], g1 = acc[ai][bj][m][1] * sv[bj][1];
;                     u32x4 w; w.x = cvt_pk_bf16(g0[0] * bf_lo(zv.x), g0[1] * bf_hi(zv.x)); w.y = cvt_pk_bf16(g0[2] * bf_lo(zv.y), g0[3] * bf_hi(zv.y));
;                     w.z = cvt_pk_bf16(g1[0] * bf_lo(zv.z), g1[1] * bf_hi(zv.z)); w.w = cvt_pk_bf16(g1[2] * bf_lo(zv.w), g1[3] * bf_hi(zv.w));
;                     *(u32x4*)(V + off + bj * HALF) = w; } }
	v_cndmask_b32_e64 v104, v104, v108, s[54:55]
	v_cndmask_b32_e64 v105, v105, v109, s[54:55]
	v_cndmask_b32_e64 v106, v106, v110, s[54:55]
	v_cndmask_b32_e64 v107, v107, v111, s[54:55]
	v_lshlrev_b32_e32 v108, 16, v104
	v_and_b32_e32 v104, 0xffff0000, v104
	v_lshlrev_b32_e32 v109, 16, v105
	v_and_b32_e32 v105, 0xffff0000, v105
	v_lshlrev_b32_e32 v110, 16, v106
	v_and_b32_e32 v106, 0xffff0000, v106
	v_lshlrev_b32_e32 v111, 16, v107
	v_and_b32_e32 v107, 0xffff0000, v107
	v_mul_f32_e32 v140, v140, v108
	v_mul_f32_e32 v141, v141, v104
	v_mul_f32_e32 v142, v142, v109
	v_mul_f32_e32 v143, v143, v105
	v_mul_f32_e32 v136, v136, v110
	v_mul_f32_e32 v137, v137, v106
	v_mul_f32_e32 v138, v138, v111
	v_mul_f32_e32 v139, v139, v107
	v_cvt_pk_bf16_f32 v140, v140, v141
	v_cvt_pk_bf16_f32 v141, v142, v143
	v_cvt_pk_bf16_f32 v142, v136, v137
	v_cvt_pk_bf16_f32 v143, v138, v139
	global_store_dwordx4 v144, v[140:143], s[12:13]
	s_waitcnt vmcnt(5)
	ds_bpermute_b32 v104, v146, v168
	ds_bpermute_b32 v108, v146, v172
	ds_bpermute_b32 v105, v146, v169
	ds_bpermute_b32 v109, v146, v173
	ds_bpermute_b32 v106, v146, v170
	ds_bpermute_b32 v110, v146, v174
	ds_bpermute_b32 v107, v146, v171
	ds_bpermute_b32 v111, v146, v175
	s_waitcnt lgkmcnt(8)
	global_load_dwordx4 v[160:163], v145, s[10:11]
	v_add_u32_e32 v156, 0x20000, v145
	global_load_dwordx4 v[164:167], v156, s[10:11]
	v_add_u32_e32 v145, 0x40000, v145
	v_cndmask_b32_e64 v128, v128, v132, s[54:55]
	v_cndmask_b32_e64 v129, v129, v133, s[54:55]
	v_cndmask_b32_e64 v130, v130, v134, s[54:55]
	v_cndmask_b32_e64 v131, v131, v135, s[54:55]
	v_lshlrev_b32_e32 v132, 16, v128
	v_and_b32_e32 v128, 0xffff0000, v128
	v_lshlrev_b32_e32 v133, 16, v129
	v_and_b32_e32 v129, 0xffff0000, v129
	v_lshlrev_b32_e32 v134, 16, v130
	v_and_b32_e32 v130, 0xffff0000, v130
	v_lshlrev_b32_e32 v135, 16, v131
	v_and_b32_e32 v131, 0xffff0000, v131
	v_mul_f32_e32 v124, v124, v132
	v_mul_f32_e32 v125, v125, v128
	v_mul_f32_e32 v126, v126, v133
	v_mul_f32_e32 v127, v127, v129
	v_mul_f32_e32 v116, v116, v134
	v_mul_f32_e32 v117, v117, v130
	v_mul_f32_e32 v118, v118, v135
	v_mul_f32_e32 v119, v119, v131
	v_cvt_pk_bf16_f32 v124, v124, v125
	v_cvt_pk_bf16_f32 v125, v126, v127
	v_cvt_pk_bf16_f32 v126, v116, v117
	v_cvt_pk_bf16_f32 v127, v118, v119
	global_store_dwordx4 v144, v[124:127], s[12:13] offset:64
	v_add_u32_e32 v144, 0x40000, v144
	ds_bpermute_b32 v128, v147, v168
	ds_bpermute_b32 v132, v147, v172
	ds_bpermute_b32 v129, v147, v169
	ds_bpermute_b32 v133, v147, v173
	ds_bpermute_b32 v130, v147, v170
	ds_bpermute_b32 v134, v147, v174
	ds_bpermute_b32 v131, v147, v171
	ds_bpermute_b32 v135, v147, v175
	s_waitcnt lgkmcnt(8)
	v_cndmask_b32_e64 v104, v104, v108, s[54:55]
	v_cndmask_b32_e64 v105, v105, v109, s[54:55]
	v_cndmask_b32_e64 v106, v106, v110, s[54:55]
	v_cndmask_b32_e64 v107, v107, v111, s[54:55]
	v_lshlrev_b32_e32 v108, 16, v104
	v_and_b32_e32 v104, 0xffff0000, v104
	v_lshlrev_b32_e32 v109, 16, v105
	v_and_b32_e32 v105, 0xffff0000, v105
	v_lshlrev_b32_e32 v110, 16, v106
	v_and_b32_e32 v106, 0xffff0000, v106
	v_lshlrev_b32_e32 v111, 16, v107
	v_and_b32_e32 v107, 0xffff0000, v107
	v_mul_f32_e32 v120, v120, v108
	v_mul_f32_e32 v121, v121, v104
	v_mul_f32_e32 v122, v122, v109
	v_mul_f32_e32 v123, v123, v105
	v_mul_f32_e32 v112, v112, v110
	v_mul_f32_e32 v113, v113, v106
	v_mul_f32_e32 v114, v114, v111
	v_mul_f32_e32 v115, v115, v107
	v_cvt_pk_bf16_f32 v120, v120, v121
	v_cvt_pk_bf16_f32 v121, v122, v123
	v_cvt_pk_bf16_f32 v122, v112, v113
	v_cvt_pk_bf16_f32 v123, v114, v115
	global_store_dwordx4 v144, v[120:123], s[12:13]
	s_waitcnt vmcnt(7)
	ds_bpermute_b32 v104, v146, v176
	ds_bpermute_b32 v108, v146, v180
	ds_bpermute_b32 v105, v146, v177
	ds_bpermute_b32 v109, v146, v181
	ds_bpermute_b32 v106, v146, v178
	ds_bpermute_b32 v110, v146, v182
	ds_bpermute_b32 v107, v146, v179
	ds_bpermute_b32 v111, v146, v183
	s_waitcnt lgkmcnt(8)
	global_load_dwordx4 v[168:171], v145, s[10:11]
	v_add_u32_e32 v156, 0x20000, v145
	global_load_dwordx4 v[172:175], v156, s[10:11]
	v_add_u32_e32 v145, 0x40000, v145
	v_cndmask_b32_e64 v128, v128, v132, s[54:55]
	v_cndmask_b32_e64 v129, v129, v133, s[54:55]
	v_cndmask_b32_e64 v130, v130, v134, s[54:55]
	v_cndmask_b32_e64 v131, v131, v135, s[54:55]
	v_lshlrev_b32_e32 v132, 16, v128
	v_and_b32_e32 v128, 0xffff0000, v128
	v_lshlrev_b32_e32 v133, 16, v129
	v_and_b32_e32 v129, 0xffff0000, v129
	v_lshlrev_b32_e32 v134, 16, v130
	v_and_b32_e32 v130, 0xffff0000, v130
	v_lshlrev_b32_e32 v135, 16, v131
	v_and_b32_e32 v131, 0xffff0000, v131
	v_mul_f32_e32 v100, v100, v132
	v_mul_f32_e32 v101, v101, v128
	v_mul_f32_e32 v102, v102, v133
	v_mul_f32_e32 v103, v103, v129
	v_mul_f32_e32 v92, v92, v134
	v_mul_f32_e32 v93, v93, v130
	v_mul_f32_e32 v94, v94, v135
	v_mul_f32_e32 v95, v95, v131
	v_cvt_pk_bf16_f32 v100, v100, v101
	v_cvt_pk_bf16_f32 v101, v102, v103
	v_cvt_pk_bf16_f32 v102, v92, v93
	v_cvt_pk_bf16_f32 v103, v94, v95
	global_store_dwordx4 v144, v[100:103], s[12:13] offset:64
	v_add_u32_e32 v144, 0x40000, v144
	ds_bpermute_b32 v128, v147, v176
	ds_bpermute_b32 v132, v147, v180
	ds_bpermute_b32 v129, v147, v177
	ds_bpermute_b32 v133, v147, v181
	ds_bpermute_b32 v130, v147, v178
	ds_bpermute_b32 v134, v147, v182
	ds_bpermute_b32 v131, v147, v179
	ds_bpermute_b32 v135, v147, v183
	s_waitcnt lgkmcnt(8)
; __device__ __forceinline__ unsigned cvt_pk_bf16(float lo, float hi) { unsigned r; asm volatile("v_cvt_pk_bf16_f32 %0, %1, %2" : "=v"(r) : "v"(lo), "v"(hi)); return r; }
; __device__ __forceinline__ float bf_lo(unsigned w) { return __uint_as_float(w << 16); }
; __device__ __forceinline__ float bf_hi(unsigned w) { return __uint_as_float(w & 0xffff0000u); }
;     __device__ __forceinline__ void operator()(const f32x4 (&acc)[2][2][4][2], const Unit& u, int wr, int wc, int fr, int fq) const {
;     ...
;         for (int ai = 0; ai < 2; ++ai)
; #pragma unroll
;             for (int m = 0; m < 4; ++m) { const size_t off = (size_t)(row0 + ai * HALF + m * 16) * EI + col0;
; #pragma unroll
;                 for (int bj = 0; bj < 2; ++bj) { const u32x4 zv = *(const u32x4*)(SZ + off + bj * HALF);
;                     const f32x4 g0 = acc[ai][bj][m][0] * sv[bj][0], g1 = acc[ai][bj][m][1] * sv[bj][1];
;                     u32x4 w; w.x = cvt_pk_bf16(g0[0] * bf_lo(zv.x), g0[1] * bf_hi(zv.x)); w.y = cvt_pk_bf16(g0[2] * bf_lo(zv.y), g0[3] * bf_hi(zv.y));
;                     w.z = cvt_pk_bf16(g1[0] * bf_lo(zv.z), g1[1] * bf_hi(zv.z)); w.w = cvt_pk_bf16(g1[2] * bf_lo(zv.w), g1[3] * bf_hi(zv.w));
;                     *(u32x4*)(V + off + bj * HALF) = w; } }
	v_cndmask_b32_e64 v104, v104, v108, s[54:55]
	v_cndmask_b32_e64 v105, v105, v109, s[54:55]
	v_cndmask_b32_e64 v106, v106, v110, s[54:55]
	v_cndmask_b32_e64 v107, v107, v111, s[54:55]
	v_lshlrev_b32_e32 v108, 16, v104
	v_and_b32_e32 v104, 0xffff0000, v104
	v_lshlrev_b32_e32 v109, 16, v105
	v_and_b32_e32 v105, 0xffff0000, v105
	v_lshlrev_b32_e32 v110, 16, v106
	v_and_b32_e32 v106, 0xffff0000, v106
	v_lshlrev_b32_e32 v111, 16, v107
	v_and_b32_e32 v107, 0xffff0000, v107
	v_mul_f32_e32 v96, v96, v108
	v_mul_f32_e32 v97, v97, v104
	v_mul_f32_e32 v98, v98, v109
	v_mul_f32_e32 v99, v99, v105
	v_mul_f32_e32 v88, v88, v110
	v_mul_f32_e32 v89, v89, v106
	v_mul_f32_e32 v90, v90, v111
	v_mul_f32_e32 v91, v91, v107
	v_cvt_pk_bf16_f32 v96, v96, v97
	v_cvt_pk_bf16_f32 v97, v98, v99
	v_cvt_pk_bf16_f32 v98, v88, v89
	v_cvt_pk_bf16_f32 v99, v90, v91
	global_store_dwordx4 v144, v[96:99], s[12:13]
	s_waitcnt vmcnt(9)
	ds_bpermute_b32 v104, v146, v184
	ds_bpermute_b32 v108, v146, v188
	ds_bpermute_b32 v105, v146, v185
	ds_bpermute_b32 v109, v146, v189
	ds_bpermute_b32 v106, v146, v186
	ds_bpermute_b32 v110, v146, v190
	ds_bpermute_b32 v107, v146, v187
	ds_bpermute_b32 v111, v146, v191
	s_waitcnt lgkmcnt(8)
	global_load_dwordx4 v[176:179], v145, s[10:11]
	v_add_u32_e32 v156, 0x20000, v145
	global_load_dwordx4 v[180:183], v156, s[10:11]
	v_add_u32_e32 v145, 0x40000, v145
	v_cndmask_b32_e64 v128, v128, v132, s[54:55]
	v_cndmask_b32_e64 v129, v129, v133, s[54:55]
	v_cndmask_b32_e64 v130, v130, v134, s[54:55]
	v_cndmask_b32_e64 v131, v131, v135, s[54:55]
	v_lshlrev_b32_e32 v132, 16, v128
	v_and_b32_e32 v128, 0xffff0000, v128
	v_lshlrev_b32_e32 v133, 16, v129
	v_and_b32_e32 v129, 0xffff0000, v129
	v_lshlrev_b32_e32 v134, 16, v130
	v_and_b32_e32 v130, 0xffff0000, v130
	v_lshlrev_b32_e32 v135, 16, v131
	v_and_b32_e32 v131, 0xffff0000, v131
	v_mul_f32_e32 v84, v84, v132
	v_mul_f32_e32 v85, v85, v128
	v_mul_f32_e32 v86, v86, v133
	v_mul_f32_e32 v87, v87, v129
	v_mul_f32_e32 v76, v76, v134
	v_mul_f32_e32 v77, v77, v130
	v_mul_f32_e32 v78, v78, v135
	v_mul_f32_e32 v79, v79, v131
	v_cvt_pk_bf16_f32 v84, v84, v85
	v_cvt_pk_bf16_f32 v85, v86, v87
	v_cvt_pk_bf16_f32 v86, v76, v77
	v_cvt_pk_bf16_f32 v87, v78, v79
	global_store_dwordx4 v144, v[84:87], s[12:13] offset:64
	v_add_u32_e32 v144, 0x40000, v144
	ds_bpermute_b32 v128, v147, v184
	ds_bpermute_b32 v132, v147, v188
	ds_bpermute_b32 v129, v147, v185
	ds_bpermute_b32 v133, v147, v189
	ds_bpermute_b32 v130, v147, v186
	ds_bpermute_b32 v134, v147, v190
	ds_bpermute_b32 v131, v147, v187
	ds_bpermute_b32 v135, v147, v191
	s_waitcnt lgkmcnt(8)
	v_cndmask_b32_e64 v104, v104, v108, s[54:55]
	v_cndmask_b32_e64 v105, v105, v109, s[54:55]
	v_cndmask_b32_e64 v106, v106, v110, s[54:55]
	v_cndmask_b32_e64 v107, v107, v111, s[54:55]
	v_lshlrev_b32_e32 v108, 16, v104
	v_and_b32_e32 v104, 0xffff0000, v104
	v_lshlrev_b32_e32 v109, 16, v105
	v_and_b32_e32 v105, 0xffff0000, v105
	v_lshlrev_b32_e32 v110, 16, v106
	v_and_b32_e32 v106, 0xffff0000, v106
	v_lshlrev_b32_e32 v111, 16, v107
	v_and_b32_e32 v107, 0xffff0000, v107
	v_mul_f32_e32 v80, v80, v108
	v_mul_f32_e32 v81, v81, v104
	v_mul_f32_e32 v82, v82, v109
	v_mul_f32_e32 v83, v83, v105
	v_mul_f32_e32 v72, v72, v110
	v_mul_f32_e32 v73, v73, v106
	v_mul_f32_e32 v74, v74, v111
	v_mul_f32_e32 v75, v75, v107
	v_cvt_pk_bf16_f32 v80, v80, v81
	v_cvt_pk_bf16_f32 v81, v82, v83
	v_cvt_pk_bf16_f32 v82, v72, v73
	v_cvt_pk_bf16_f32 v83, v74, v75
	global_store_dwordx4 v144, v[80:83], s[12:13]
	s_waitcnt vmcnt(10)
	ds_bpermute_b32 v104, v146, v160
	ds_bpermute_b32 v108, v146, v164
	ds_bpermute_b32 v105, v146, v161
	ds_bpermute_b32 v109, v146, v165
	ds_bpermute_b32 v106, v146, v162
	ds_bpermute_b32 v110, v146, v166
	ds_bpermute_b32 v107, v146, v163
	ds_bpermute_b32 v111, v146, v167
	s_waitcnt lgkmcnt(8)
	global_load_dwordx4 v[184:187], v145, s[10:11]
	v_add_u32_e32 v156, 0x20000, v145
	global_load_dwordx4 v[188:191], v156, s[10:11]
	v_cndmask_b32_e64 v128, v128, v132, s[54:55]
	v_cndmask_b32_e64 v129, v129, v133, s[54:55]
	v_cndmask_b32_e64 v130, v130, v134, s[54:55]
	v_cndmask_b32_e64 v131, v131, v135, s[54:55]
	v_lshlrev_b32_e32 v132, 16, v128
	v_and_b32_e32 v128, 0xffff0000, v128
	v_lshlrev_b32_e32 v133, 16, v129
	v_and_b32_e32 v129, 0xffff0000, v129
	v_lshlrev_b32_e32 v134, 16, v130
	v_and_b32_e32 v130, 0xffff0000, v130
	v_lshlrev_b32_e32 v135, 16, v131
	v_and_b32_e32 v131, 0xffff0000, v131
	v_mul_f32_e32 v68, v68, v132
	v_mul_f32_e32 v69, v69, v128
	v_mul_f32_e32 v70, v70, v133
	v_mul_f32_e32 v71, v71, v129
	v_mul_f32_e32 v64, v64, v134
	v_mul_f32_e32 v65, v65, v130
	v_mul_f32_e32 v66, v66, v135
	v_mul_f32_e32 v67, v67, v131
	v_cvt_pk_bf16_f32 v68, v68, v69
	v_cvt_pk_bf16_f32 v69, v70, v71
	v_cvt_pk_bf16_f32 v70, v64, v65
	v_cvt_pk_bf16_f32 v71, v66, v67
	global_store_dwordx4 v144, v[68:71], s[12:13] offset:64
	v_add_u32_e32 v144, 0x140000, v144
	ds_bpermute_b32 v128, v147, v160
	ds_bpermute_b32 v132, v147, v164
	ds_bpermute_b32 v129, v147, v161
	ds_bpermute_b32 v133, v147, v165
	ds_bpermute_b32 v130, v147, v162
	ds_bpermute_b32 v134, v147, v166
	ds_bpermute_b32 v131, v147, v163
	ds_bpermute_b32 v135, v147, v167
	s_waitcnt lgkmcnt(8)
	v_cndmask_b32_e64 v104, v104, v108, s[54:55]
	v_cndmask_b32_e64 v105, v105, v109, s[54:55]
	v_cndmask_b32_e64 v106, v106, v110, s[54:55]
	v_cndmask_b32_e64 v107, v107, v111, s[54:55]
	v_lshlrev_b32_e32 v108, 16, v104
	v_and_b32_e32 v104, 0xffff0000, v104
	v_lshlrev_b32_e32 v109, 16, v105
	v_and_b32_e32 v105, 0xffff0000, v105
	v_lshlrev_b32_e32 v110, 16, v106
	v_and_b32_e32 v106, 0xffff0000, v106
	v_lshlrev_b32_e32 v111, 16, v107
	v_and_b32_e32 v107, 0xffff0000, v107
	v_mul_f32_e32 v60, v60, v108
	v_mul_f32_e32 v61, v61, v104
	v_mul_f32_e32 v62, v62, v109
	v_mul_f32_e32 v63, v63, v105
	v_mul_f32_e32 v56, v56, v110
	v_mul_f32_e32 v57, v57, v106
	v_mul_f32_e32 v58, v58, v111
	v_mul_f32_e32 v59, v59, v107
	v_cvt_pk_bf16_f32 v60, v60, v61
	v_cvt_pk_bf16_f32 v61, v62, v63
	v_cvt_pk_bf16_f32 v62, v56, v57
	v_cvt_pk_bf16_f32 v63, v58, v59
	global_store_dwordx4 v144, v[60:63], s[12:13]
	s_waitcnt vmcnt(10)
; __device__ __forceinline__ unsigned cvt_pk_bf16(float lo, float hi) { unsigned r; asm volatile("v_cvt_pk_bf16_f32 %0, %1, %2" : "=v"(r) : "v"(lo), "v"(hi)); return r; }
; __device__ __forceinline__ float bf_lo(unsigned w) { return __uint_as_float(w << 16); }
; __device__ __forceinline__ float bf_hi(unsigned w) { return __uint_as_float(w & 0xffff0000u); }
;     __device__ __forceinline__ void operator()(const f32x4 (&acc)[2][2][4][2], const Unit& u, int wr, int wc, int fr, int fq) const {
;     ...
;         for (int ai = 0; ai < 2; ++ai)
; #pragma unroll
;             for (int m = 0; m < 4; ++m) { const size_t off = (size_t)(row0 + ai * HALF + m * 16) * EI + col0;
; #pragma unroll
;                 for (int bj = 0; bj < 2; ++bj) { const u32x4 zv = *(const u32x4*)(SZ + off + bj * HALF);
;                     const f32x4 g0 = acc[ai][bj][m][0] * sv[bj][0], g1 = acc[ai][bj][m][1] * sv[bj][1];
;                     u32x4 w; w.x = cvt_pk_bf16(g0[0] * bf_lo(zv.x), g0[1] * bf_hi(zv.x)); w.y = cvt_pk_bf16(g0[2] * bf_lo(zv.y), g0[3] * bf_hi(zv.y));
;                     w.z = cvt_pk_bf16(g1[0] * bf_lo(zv.z), g1[1] * bf_hi(zv.z)); w.w = cvt_pk_bf16(g1[2] * bf_lo(zv.w), g1[3] * bf_hi(zv.w));
;                     *(u32x4*)(V + off + bj * HALF) = w; } }
	ds_bpermute_b32 v104, v146, v168
	ds_bpermute_b32 v108, v146, v172
	ds_bpermute_b32 v105, v146, v169
	ds_bpermute_b32 v109, v146, v173
	ds_bpermute_b32 v106, v146, v170
	ds_bpermute_b32 v110, v146, v174
	ds_bpermute_b32 v107, v146, v171
	ds_bpermute_b32 v111, v146, v175
	s_waitcnt lgkmcnt(8)
	v_cndmask_b32_e64 v128, v128, v132, s[54:55]
	v_cndmask_b32_e64 v129, v129, v133, s[54:55]
	v_cndmask_b32_e64 v130, v130, v134, s[54:55]
	v_cndmask_b32_e64 v131, v131, v135, s[54:55]
	v_lshlrev_b32_e32 v132, 16, v128
	v_and_b32_e32 v128, 0xffff0000, v128
	v_lshlrev_b32_e32 v133, 16, v129
	v_and_b32_e32 v129, 0xffff0000, v129
	v_lshlrev_b32_e32 v134, 16, v130
	v_and_b32_e32 v130, 0xffff0000, v130
	v_lshlrev_b32_e32 v135, 16, v131
	v_and_b32_e32 v131, 0xffff0000, v131
	v_mul_f32_e32 v52, v52, v132
	v_mul_f32_e32 v53, v53, v128
	v_mul_f32_e32 v54, v54, v133
	v_mul_f32_e32 v55, v55, v129
	v_mul_f32_e32 v44, v44, v134
	v_mul_f32_e32 v45, v45, v130
	v_mul_f32_e32 v46, v46, v135
	v_mul_f32_e32 v47, v47, v131
	v_cvt_pk_bf16_f32 v52, v52, v53
	v_cvt_pk_bf16_f32 v53, v54, v55
	v_cvt_pk_bf16_f32 v54, v44, v45
	v_cvt_pk_bf16_f32 v55, v46, v47
	global_store_dwordx4 v144, v[52:55], s[12:13] offset:64
	v_add_u32_e32 v144, 0x40000, v144
	ds_bpermute_b32 v128, v147, v168
	ds_bpermute_b32 v132, v147, v172
	ds_bpermute_b32 v129, v147, v169
	ds_bpermute_b32 v133, v147, v173
	ds_bpermute_b32 v130, v147, v170
	ds_bpermute_b32 v134, v147, v174
	ds_bpermute_b32 v131, v147, v171
	ds_bpermute_b32 v135, v147, v175
	s_waitcnt lgkmcnt(8)
	v_cndmask_b32_e64 v104, v104, v108, s[54:55]
	v_cndmask_b32_e64 v105, v105, v109, s[54:55]
	v_cndmask_b32_e64 v106, v106, v110, s[54:55]
	v_cndmask_b32_e64 v107, v107, v111, s[54:55]
	v_lshlrev_b32_e32 v108, 16, v104
	v_and_b32_e32 v104, 0xffff0000, v104
	v_lshlrev_b32_e32 v109, 16, v105
	v_and_b32_e32 v105, 0xffff0000, v105
	v_lshlrev_b32_e32 v110, 16, v106
	v_and_b32_e32 v106, 0xffff0000, v106
	v_lshlrev_b32_e32 v111, 16, v107
	v_and_b32_e32 v107, 0xffff0000, v107
	v_mul_f32_e32 v48, v48, v108
	v_mul_f32_e32 v49, v49, v104
	v_mul_f32_e32 v50, v50, v109
	v_mul_f32_e32 v51, v51, v105
	v_mul_f32_e32 v40, v40, v110
	v_mul_f32_e32 v41, v41, v106
	v_mul_f32_e32 v42, v42, v111
	v_mul_f32_e32 v43, v43, v107
	v_cvt_pk_bf16_f32 v48, v48, v49
	v_cvt_pk_bf16_f32 v49, v50, v51
	v_cvt_pk_bf16_f32 v50, v40, v41
	v_cvt_pk_bf16_f32 v51, v42, v43
	global_store_dwordx4 v144, v[48:51], s[12:13]
	s_waitcnt vmcnt(8)
	ds_bpermute_b32 v104, v146, v176
	ds_bpermute_b32 v108, v146, v180
	ds_bpermute_b32 v105, v146, v177
	ds_bpermute_b32 v109, v146, v181
	ds_bpermute_b32 v106, v146, v178
	ds_bpermute_b32 v110, v146, v182
	ds_bpermute_b32 v107, v146, v179
	ds_bpermute_b32 v111, v146, v183
	s_waitcnt lgkmcnt(8)
	v_cndmask_b32_e64 v128, v128, v132, s[54:55]
	v_cndmask_b32_e64 v129, v129, v133, s[54:55]
	v_cndmask_b32_e64 v130, v130, v134, s[54:55]
	v_cndmask_b32_e64 v131, v131, v135, s[54:55]
	v_lshlrev_b32_e32 v132, 16, v128
	v_and_b32_e32 v128, 0xffff0000, v128
	v_lshlrev_b32_e32 v133, 16, v129
	v_and_b32_e32 v129, 0xffff0000, v129
	v_lshlrev_b32_e32 v134, 16, v130
	v_and_b32_e32 v130, 0xffff0000, v130
	v_lshlrev_b32_e32 v135, 16, v131
	v_and_b32_e32 v131, 0xffff0000, v131
	v_mul_f32_e32 v36, v36, v132
	v_mul_f32_e32 v37, v37, v128
	v_mul_f32_e32 v38, v38, v133
	v_mul_f32_e32 v39, v39, v129
	v_mul_f32_e32 v28, v28, v134
	v_mul_f32_e32 v29, v29, v130
	v_mul_f32_e32 v30, v30, v135
	v_mul_f32_e32 v31, v31, v131
	v_cvt_pk_bf16_f32 v36, v36, v37
	v_cvt_pk_bf16_f32 v37, v38, v39
	v_cvt_pk_bf16_f32 v38, v28, v29
	v_cvt_pk_bf16_f32 v39, v30, v31
	global_store_dwordx4 v144, v[36:39], s[12:13] offset:64
	v_add_u32_e32 v144, 0x40000, v144
	ds_bpermute_b32 v128, v147, v176
	ds_bpermute_b32 v132, v147, v180
	ds_bpermute_b32 v129, v147, v177
	ds_bpermute_b32 v133, v147, v181
	ds_bpermute_b32 v130, v147, v178
	ds_bpermute_b32 v134, v147, v182
	ds_bpermute_b32 v131, v147, v179
	ds_bpermute_b32 v135, v147, v183
	s_waitcnt lgkmcnt(8)
; __device__ __forceinline__ unsigned cvt_pk_bf16(float lo, float hi) { unsigned r; asm volatile("v_cvt_pk_bf16_f32 %0, %1, %2" : "=v"(r) : "v"(lo), "v"(hi)); return r; }
; __device__ __forceinline__ float bf_lo(unsigned w) { return __uint_as_float(w << 16); }
; __device__ __forceinline__ float bf_hi(unsigned w) { return __uint_as_float(w & 0xffff0000u); }
; #define PG8_BAR __builtin_amdgcn_s_barrier()
;     __device__ __forceinline__ void operator()(const f32x4 (&acc)[2][2][4][2], const Unit& u, int wr, int wc, int fr, int fq) const {
;     ...
;         for (int ai = 0; ai < 2; ++ai)
; #pragma unroll
;             for (int m = 0; m < 4; ++m) { const size_t off = (size_t)(row0 + ai * HALF + m * 16) * EI + col0;
; #pragma unroll
;                 for (int bj = 0; bj < 2; ++bj) { const u32x4 zv = *(const u32x4*)(SZ + off + bj * HALF);
;                     const f32x4 g0 = acc[ai][bj][m][0] * sv[bj][0], g1 = acc[ai][bj][m][1] * sv[bj][1];
;                     u32x4 w; w.x = cvt_pk_bf16(g0[0] * bf_lo(zv.x), g0[1] * bf_hi(zv.x)); w.y = cvt_pk_bf16(g0[2] * bf_lo(zv.y), g0[3] * bf_hi(zv.y));
;                     w.z = cvt_pk_bf16(g1[0] * bf_lo(zv.z), g1[1] * bf_hi(zv.z)); w.w = cvt_pk_bf16(g1[2] * bf_lo(zv.w), g1[3] * bf_hi(zv.w));
;                     *(u32x4*)(V + off + bj * HALF) = w; } }
; template <class Epi, class Sched>
; __device__ __forceinline__ void gemm_phase(PG8_LAS unsigned char* lds, const Gemm g, const Sched& S, const Epi& E, int wave_) {
;     ...
;         E(acc, cur, wr, wc, fr, fq);
;         if (!has_next) break;
; #pragma unroll
;         for (int a = 0; a < 2; ++a)
; #pragma unroll
;             for (int b = 0; b < 2; ++b)
; #pragma unroll
;                 for (int m = 0; m < 4; ++m)
; #pragma unroll
;                     for (int n = 0; n < 2; ++n) acc[a][b][m][n] = (f32x4){0.f, 0.f, 0.f, 0.f};
;         cur = nxt; cA = nA; cB = nB; ++ui;
;         if (wr == 1) PG8_BAR;
;     }
	v_cndmask_b32_e64 v104, v104, v108, s[54:55]
	v_cndmask_b32_e64 v105, v105, v109, s[54:55]
	v_cndmask_b32_e64 v106, v106, v110, s[54:55]
	v_cndmask_b32_e64 v107, v107, v111, s[54:55]
	v_lshlrev_b32_e32 v108, 16, v104
	v_and_b32_e32 v104, 0xffff0000, v104
	v_lshlrev_b32_e32 v109, 16, v105
	v_and_b32_e32 v105, 0xffff0000, v105
	v_lshlrev_b32_e32 v110, 16, v106
	v_and_b32_e32 v106, 0xffff0000, v106
	v_lshlrev_b32_e32 v111, 16, v107
	v_and_b32_e32 v107, 0xffff0000, v107
	v_mul_f32_e32 v32, v32, v108
	v_mul_f32_e32 v33, v33, v104
	v_mul_f32_e32 v34, v34, v109
	v_mul_f32_e32 v35, v35, v105
	v_mul_f32_e32 v24, v24, v110
	v_mul_f32_e32 v25, v25, v106
	v_mul_f32_e32 v26, v26, v111
	v_mul_f32_e32 v27, v27, v107
	v_cvt_pk_bf16_f32 v32, v32, v33
	v_cvt_pk_bf16_f32 v33, v34, v35
	v_cvt_pk_bf16_f32 v34, v24, v25
	v_cvt_pk_bf16_f32 v35, v26, v27
	global_store_dwordx4 v144, v[32:35], s[12:13]
	s_waitcnt vmcnt(6)
	ds_bpermute_b32 v104, v146, v184
	ds_bpermute_b32 v108, v146, v188
	ds_bpermute_b32 v105, v146, v185
	ds_bpermute_b32 v109, v146, v189
	ds_bpermute_b32 v106, v146, v186
	ds_bpermute_b32 v110, v146, v190
	ds_bpermute_b32 v107, v146, v187
	ds_bpermute_b32 v111, v146, v191
	s_waitcnt lgkmcnt(8)
	v_cndmask_b32_e64 v128, v128, v132, s[54:55]
	v_cndmask_b32_e64 v129, v129, v133, s[54:55]
	v_cndmask_b32_e64 v130, v130, v134, s[54:55]
	v_cndmask_b32_e64 v131, v131, v135, s[54:55]
	v_lshlrev_b32_e32 v132, 16, v128
	v_and_b32_e32 v128, 0xffff0000, v128
	v_lshlrev_b32_e32 v133, 16, v129
	v_and_b32_e32 v129, 0xffff0000, v129
	v_lshlrev_b32_e32 v134, 16, v130
	v_and_b32_e32 v130, 0xffff0000, v130
	v_lshlrev_b32_e32 v135, 16, v131
	v_and_b32_e32 v131, 0xffff0000, v131
	v_mul_f32_e32 v20, v20, v132
	v_mul_f32_e32 v21, v21, v128
	v_mul_f32_e32 v22, v22, v133
	v_mul_f32_e32 v23, v23, v129
	v_mul_f32_e32 v12, v12, v134
	v_mul_f32_e32 v13, v13, v130
	v_mul_f32_e32 v14, v14, v135
	v_mul_f32_e32 v15, v15, v131
	v_cvt_pk_bf16_f32 v20, v20, v21
	v_cvt_pk_bf16_f32 v21, v22, v23
	v_cvt_pk_bf16_f32 v22, v12, v13
	v_cvt_pk_bf16_f32 v23, v14, v15
	global_store_dwordx4 v144, v[20:23], s[12:13] offset:64
	v_add_u32_e32 v144, 0x40000, v144
	ds_bpermute_b32 v128, v147, v184
	ds_bpermute_b32 v132, v147, v188
	ds_bpermute_b32 v129, v147, v185
	ds_bpermute_b32 v133, v147, v189
	ds_bpermute_b32 v130, v147, v186
	ds_bpermute_b32 v134, v147, v190
	ds_bpermute_b32 v131, v147, v187
	ds_bpermute_b32 v135, v147, v191
	s_waitcnt lgkmcnt(8)
	v_cndmask_b32_e64 v104, v104, v108, s[54:55]
	v_cndmask_b32_e64 v105, v105, v109, s[54:55]
	v_cndmask_b32_e64 v106, v106, v110, s[54:55]
	v_cndmask_b32_e64 v107, v107, v111, s[54:55]
	v_lshlrev_b32_e32 v108, 16, v104
	v_and_b32_e32 v104, 0xffff0000, v104
	v_lshlrev_b32_e32 v109, 16, v105
	v_and_b32_e32 v105, 0xffff0000, v105
	v_lshlrev_b32_e32 v110, 16, v106
	v_and_b32_e32 v106, 0xffff0000, v106
	v_lshlrev_b32_e32 v111, 16, v107
	v_and_b32_e32 v107, 0xffff0000, v107
	v_mul_f32_e32 v16, v16, v108
	v_mul_f32_e32 v17, v17, v104
	v_mul_f32_e32 v18, v18, v109
	v_mul_f32_e32 v19, v19, v105
	v_mul_f32_e32 v8, v8, v110
	v_mul_f32_e32 v9, v9, v106
	v_mul_f32_e32 v10, v10, v111
	v_mul_f32_e32 v11, v11, v107
	v_cvt_pk_bf16_f32 v16, v16, v17
	v_cvt_pk_bf16_f32 v17, v18, v19
	v_cvt_pk_bf16_f32 v18, v8, v9
	v_cvt_pk_bf16_f32 v19, v10, v11
	global_store_dwordx4 v144, v[16:19], s[12:13]
	s_waitcnt lgkmcnt(0)
	v_cndmask_b32_e64 v128, v128, v132, s[54:55]
	v_cndmask_b32_e64 v129, v129, v133, s[54:55]
	v_cndmask_b32_e64 v130, v130, v134, s[54:55]
	v_cndmask_b32_e64 v131, v131, v135, s[54:55]
	v_lshlrev_b32_e32 v132, 16, v128
	v_and_b32_e32 v128, 0xffff0000, v128
	v_lshlrev_b32_e32 v133, 16, v129
	v_and_b32_e32 v129, 0xffff0000, v129
	v_lshlrev_b32_e32 v134, 16, v130
	v_and_b32_e32 v130, 0xffff0000, v130
	v_lshlrev_b32_e32 v135, 16, v131
	v_and_b32_e32 v131, 0xffff0000, v131
	v_mul_f32_e32 v4, v4, v132
	v_mul_f32_e32 v5, v5, v128
	v_mul_f32_e32 v6, v6, v133
	v_mul_f32_e32 v7, v7, v129
	v_mul_f32_e32 v0, v0, v134
	v_mul_f32_e32 v1, v1, v130
	v_mul_f32_e32 v2, v2, v135
	v_mul_f32_e32 v3, v3, v131
	v_cvt_pk_bf16_f32 v4, v4, v5
	v_cvt_pk_bf16_f32 v5, v6, v7
	v_cvt_pk_bf16_f32 v6, v0, v1
	v_cvt_pk_bf16_f32 v7, v2, v3
	global_store_dwordx4 v144, v[4:7], s[12:13] offset:64
	s_cbranch_vccnz .LBB0_1030
	s_andn2_b64 vcc, exec, s[4:5]
	s_cbranch_vccnz .LBB0_1029
	s_barrier
	s_branch .LBB0_1029
